# gates epilogue: conv-output loads hoisted one group ahead so no wait sits behind the write-through stores (on top of the VALU folds)
# speedup vs baseline: 1.0063x; 1.0063x over previous
.LBB0_461:
	v_lshl_or_b32 v166, s78, 7, v172
	v_ashrrev_i32_e32 v167, 31, v166
	v_readlane_b32 s4, v254, 4
	v_lshlrev_b64 v[144:145], 2, v[166:167]
	v_readlane_b32 s5, v254, 5
	v_readlane_b32 s6, v254, 6
	v_readlane_b32 s7, v254, 7
	v_readlane_b32 s8, v254, 8
	v_readlane_b32 s9, v254, 9
	v_readlane_b32 s10, v254, 10
	v_readlane_b32 s11, v254, 11
	v_readlane_b32 s12, v254, 12
	v_readlane_b32 s13, v254, 13
	v_readlane_b32 s14, v254, 14
	v_readlane_b32 s15, v254, 15
	v_readlane_b32 s16, v254, 16
	v_readlane_b32 s17, v254, 17
	v_readlane_b32 s18, v254, 18
	v_readlane_b32 s19, v254, 19
	v_lshl_add_u64 v[32:33], s[16:17], 0, v[144:145]
	v_readlane_b32 s4, v254, 21
	v_readlane_b32 s5, v254, 22
	v_readlane_b32 s6, v254, 23
	v_readlane_b32 s7, v254, 24
	v_lshl_add_u64 v[44:45], s[4:5], 0, v[144:145]
	global_load_dwordx4 v[28:31], v[32:33], off offset:16
	global_load_dwordx4 v[40:43], v[32:33], off
	v_lshl_add_u64 v[148:149], s[6:7], 0, v[144:145]
	global_load_dwordx4 v[32:35], v[44:45], off offset:16
	s_nop 0
	global_load_dwordx4 v[44:47], v[44:45], off
	s_nop 0
	global_load_dwordx4 v[144:147], v[148:149], off offset:16
	s_nop 0
	v_and_b32_e32 v244, 31, v152
	v_lshlrev_b32_e32 v244, 2, v244
	v_lshrrev_b32_e32 v245, 4, v152
	v_lshlrev_b32_e32 v245, 5, v245
	v_sub_u32_e32 v244, v244, v245
	v_ashrrev_i32_e32 v245, 31, v244
	v_lshl_add_u64 v[244:245], v[148:149], 0, v[244:245]
	global_load_dword v148, v[244:245], off
	v_lshl_add_u32 v168, s0, 8, v170
	v_readlane_b32 s8, v254, 25
	v_readlane_b32 s9, v254, 26
	s_mov_b64 s[8:9], 0x40000
	v_readlane_b32 s10, v254, 27
	v_readlane_b32 s11, v254, 28
	v_readlane_b32 s12, v254, 29
	v_readlane_b32 s13, v254, 30
	v_readlane_b32 s14, v254, 31
	v_readlane_b32 s15, v254, 32
	v_readlane_b32 s16, v254, 33
	v_readlane_b32 s17, v254, 34
	v_readlane_b32 s18, v254, 35
	v_readlane_b32 s19, v254, 36
	s_waitcnt vmcnt(0)
	v_mul_f32_e32 v28, 0xbfb8aa3b, v28
	v_mul_f32_e32 v29, 0xbfb8aa3b, v29
	v_mul_f32_e32 v30, 0xbfb8aa3b, v30
	v_mul_f32_e32 v31, 0xbfb8aa3b, v31
	v_mul_f32_e32 v32, 0xbfb8aa3b, v32
	v_mul_f32_e32 v33, 0xbfb8aa3b, v33
	v_mul_f32_e32 v34, 0xbfb8aa3b, v34
	v_mul_f32_e32 v35, 0xbfb8aa3b, v35
	v_mul_f32_e32 v40, 0xbfb8aa3b, v40
	v_mul_f32_e32 v41, 0xbfb8aa3b, v41
	v_mul_f32_e32 v42, 0xbfb8aa3b, v42
	v_mul_f32_e32 v43, 0xbfb8aa3b, v43
	v_mul_f32_e32 v44, 0xbfb8aa3b, v44
	v_mul_f32_e32 v45, 0xbfb8aa3b, v45
	v_mul_f32_e32 v46, 0xbfb8aa3b, v46
	v_mul_f32_e32 v47, 0xbfb8aa3b, v47
	v_fmamk_f32 v140, v140, 0xbfb8aa3b, v40
	v_mul_f32_e32 v144, 0xbfb8aa3b, v144
	v_mul_f32_e32 v148, 0xbfb8aa3b, v148
	v_exp_f32_e32 v148, v148
	v_exp_f32_e32 v144, v144
	v_exp_f32_e32 v140, v140
	v_add_f32_e32 v169, 1.0, v148
	v_add_f32_e32 v187, -1.0, v169
	v_sub_f32_e32 v188, v187, v169
	v_add_f32_e32 v188, 1.0, v188
	v_sub_f32_e32 v187, v148, v187
	v_add_f32_e32 v187, v187, v188
	v_frexp_mant_f32_e32 v188, v169
	v_cmp_gt_f32_e32 vcc, s93, v188
	v_cvt_f64_f32_e32 v[188:189], v169
	v_frexp_exp_i32_f64_e32 v188, v[188:189]
	v_subbrev_co_u32_e32 v188, vcc, 0, v188, vcc
	v_sub_u32_e32 v189, 0, v188
	v_ldexp_f32 v169, v169, v189
	v_ldexp_f32 v187, v187, v189
	v_add_f32_e32 v189, -1.0, v169
	v_add_f32_e32 v190, 1.0, v189
	v_sub_f32_e32 v190, v169, v190
	v_add_f32_e32 v190, v187, v190
	v_add_f32_e32 v191, v189, v190
	v_sub_f32_e32 v189, v191, v189
	v_sub_f32_e32 v189, v190, v189
	v_add_f32_e32 v190, 1.0, v169
	v_add_f32_e32 v192, -1.0, v190
	v_sub_f32_e32 v169, v169, v192
	v_add_f32_e32 v169, v187, v169
	v_add_f32_e32 v187, v190, v169
	v_sub_f32_e32 v190, v187, v190
	v_sub_f32_e32 v169, v169, v190
	v_rcp_f32_e32 v190, v187
	v_cvt_f32_i32_e32 v188, v188
	v_cmp_neq_f32_e32 vcc, s95, v148
	v_add_f32_e32 v140, 1.0, v140
	v_mul_f32_e32 v192, v191, v190
	v_mul_f32_e32 v193, v187, v192
	v_fma_f32 v194, v192, v187, -v193
	v_fmac_f32_e32 v194, v192, v169
	v_add_f32_e32 v195, v193, v194
	v_sub_f32_e32 v196, v191, v195
	v_sub_f32_e32 v191, v191, v196
	v_sub_f32_e32 v193, v195, v193
	v_sub_f32_e32 v191, v191, v195
	v_add_f32_e32 v189, v189, v191
	v_sub_f32_e32 v191, v193, v194
	v_add_f32_e32 v189, v191, v189
	v_add_f32_e32 v191, v196, v189
	v_mul_f32_e32 v193, v190, v191
	v_mul_f32_e32 v194, v187, v193
	v_fma_f32 v187, v193, v187, -v194
	v_fmac_f32_e32 v187, v193, v169
	v_sub_f32_e32 v169, v196, v191
	v_add_f32_e32 v169, v189, v169
	v_add_f32_e32 v189, v194, v187
	v_sub_f32_e32 v195, v191, v189
	v_sub_f32_e32 v191, v191, v195
	v_sub_f32_e32 v194, v189, v194
	v_sub_f32_e32 v189, v191, v189
	v_add_f32_e32 v169, v169, v189
	v_sub_f32_e32 v187, v194, v187
	v_add_f32_e32 v169, v187, v169
	v_add_f32_e32 v187, v192, v193
	v_add_f32_e32 v169, v195, v169
	v_sub_f32_e32 v189, v187, v192
	v_mul_f32_e32 v169, v190, v169
	v_sub_f32_e32 v189, v193, v189
	v_add_f32_e32 v169, v189, v169
	v_mul_f32_e32 v192, 0x3f317218, v188
	v_add_f32_e32 v189, v187, v169
	v_fma_f32 v193, v188, s94, -v192
	v_mul_f32_e32 v190, v189, v189
	v_fmac_f32_e32 v193, 0xb102e308, v188
	v_sub_f32_e32 v187, v189, v187
	v_fmamk_f32 v191, v190, 0x3e9b6dac, v183
	v_sub_f32_e32 v169, v169, v187
	v_add_f32_e32 v187, v192, v193
	v_fmaak_f32 v191, v190, v191, 0x3f2aaada
	v_sub_f32_e32 v188, v187, v192
	v_ldexp_f32 v192, v189, 1
	v_mul_f32_e32 v189, v189, v190
	v_mul_f32_e32 v189, v189, v191
	v_add_f32_e32 v190, v192, v189
	v_sub_f32_e32 v191, v190, v192
	v_ldexp_f32 v169, v169, 1
	v_sub_f32_e32 v189, v189, v191
	v_add_f32_e32 v169, v169, v189
	v_add_f32_e32 v189, v190, v169
	v_sub_f32_e32 v190, v189, v190
	v_sub_f32_e32 v169, v169, v190
	v_add_f32_e32 v190, v187, v189
	v_sub_f32_e32 v191, v190, v187
	v_sub_f32_e32 v192, v190, v191
	v_sub_f32_e32 v188, v193, v188
	v_sub_f32_e32 v187, v187, v192
	v_sub_f32_e32 v189, v189, v191
	v_add_f32_e32 v187, v189, v187
	v_add_f32_e32 v189, v188, v169
	v_sub_f32_e32 v191, v189, v188
	v_sub_f32_e32 v192, v189, v191
	v_sub_f32_e32 v188, v188, v192
	v_sub_f32_e32 v169, v169, v191
	v_add_f32_e32 v187, v189, v187
	v_add_f32_e32 v169, v169, v188
	v_add_f32_e32 v188, v190, v187
	v_sub_f32_e32 v189, v188, v190
	v_sub_f32_e32 v187, v187, v189
	v_add_f32_e32 v169, v169, v187
	v_add_f32_e32 v169, v188, v169
	v_cndmask_b32_e32 v169, v184, v169, vcc
	v_cmp_ngt_f32_e32 vcc, -1.0, v148
	v_rcp_f32_e32 v140, v140
	v_fmamk_f32 v136, v136, 0xbfb8aa3b, v44
	v_cndmask_b32_e32 v169, v185, v169, vcc
	v_cmp_neq_f32_e32 vcc, -1.0, v148
	v_exp_f32_e32 v136, v136
	v_cndmask_b32_e32 v169, v186, v169, vcc
	v_cmp_lt_f32_e64 vcc, |v148|, s96
	v_add_f32_e32 v136, 1.0, v136
	v_rcp_f32_e32 v136, v136
	v_cndmask_b32_e32 v148, v169, v148, vcc
	v_add_f32_e32 v169, 1.0, v144
	v_mul_f32_e32 v187, 0xc1000000, v148
	v_lshrrev_b32_e32 v244, 4, v152
	v_lshlrev_b32_e32 v244, 5, v244
	ds_bpermute_b32 v236, v244, v187
	v_add_u32_e32 v245, 4, v244
	ds_bpermute_b32 v237, v245, v187
	v_add_u32_e32 v245, 8, v244
	ds_bpermute_b32 v238, v245, v187
	v_add_u32_e32 v245, 12, v244
	ds_bpermute_b32 v239, v245, v187
	v_add_u32_e32 v245, 16, v244
	ds_bpermute_b32 v240, v245, v187
	v_add_u32_e32 v245, 20, v244
	ds_bpermute_b32 v241, v245, v187
	v_add_u32_e32 v245, 24, v244
	ds_bpermute_b32 v242, v245, v187
	v_add_u32_e32 v245, 28, v244
	ds_bpermute_b32 v243, v245, v187
	s_waitcnt lgkmcnt(0)
	v_mul_f32_e32 v236, 0x3fb8aa3b, v236
	v_mul_f32_e32 v237, 0x3fb8aa3b, v237
	v_mul_f32_e32 v238, 0x3fb8aa3b, v238
	v_mul_f32_e32 v239, 0x3fb8aa3b, v239
	v_mul_f32_e32 v240, 0x3fb8aa3b, v240
	v_mul_f32_e32 v241, 0x3fb8aa3b, v241
	v_mul_f32_e32 v242, 0x3fb8aa3b, v242
	v_mul_f32_e32 v243, 0x3fb8aa3b, v243
	v_mov_b32_e32 v187, v236
	v_mul_f32_e32 v140, v140, v187
	v_exp_f32_e32 v140, v140
	v_fmamk_f32 v137, v137, 0xbfb8aa3b, v45
	v_exp_f32_e32 v137, v137
	s_nop 0
	v_add_f32_e32 v137, 1.0, v137
	v_rcp_f32_e32 v137, v137
	v_mov_b32_e32 v188, v240
	v_fmamk_f32 v138, v138, 0xbfb8aa3b, v46
	v_exp_f32_e32 v138, v138
	v_fmamk_f32 v132, v132, 0xbfb8aa3b, v28
	v_add_f32_e32 v138, 1.0, v138
	v_rcp_f32_e32 v138, v138
	v_exp_f32_e32 v132, v132
	s_nop 0
	v_add_f32_e32 v132, 1.0, v132
	v_fmamk_f32 v139, v139, 0xbfb8aa3b, v47
	v_rcp_f32_e32 v132, v132
	v_mov_b32_e32 v190, v237
	v_exp_f32_e32 v139, v139
	v_mul_f32_e32 v132, v132, v188
	v_add_f32_e32 v139, 1.0, v139
	v_rcp_f32_e32 v139, v139
	v_exp_f32_e32 v132, v132
	v_fmamk_f32 v128, v128, 0xbfb8aa3b, v32
	v_exp_f32_e32 v128, v128
	v_mov_b32_e32 v189, v241
	v_add_f32_e32 v128, 1.0, v128
	v_rcp_f32_e32 v128, v128
	v_fmamk_f32 v129, v129, 0xbfb8aa3b, v33
	v_exp_f32_e32 v129, v129
	s_nop 0
	v_add_f32_e32 v129, 1.0, v129
	v_rcp_f32_e32 v129, v129
	v_fmamk_f32 v124, v124, 0xbfb8aa3b, v40
	v_exp_f32_e32 v124, v124
	v_mov_b32_e32 v191, v238
	v_add_f32_e32 v124, 1.0, v124
	v_rcp_f32_e32 v124, v124
	v_fmamk_f32 v120, v120, 0xbfb8aa3b, v44
	v_mul_f32_e32 v124, v124, v187
	v_exp_f32_e32 v124, v124
	v_exp_f32_e32 v120, v120
	s_nop 0
	v_add_f32_e32 v120, 1.0, v120
	v_rcp_f32_e32 v120, v120
	v_mov_b32_e32 v150, v242
	v_fmamk_f32 v121, v121, 0xbfb8aa3b, v45
	v_exp_f32_e32 v121, v121
	s_nop 0
	v_add_f32_e32 v121, 1.0, v121
	v_rcp_f32_e32 v121, v121
	v_fmamk_f32 v122, v122, 0xbfb8aa3b, v46
	v_exp_f32_e32 v122, v122
	s_nop 0
	v_add_f32_e32 v122, 1.0, v122
	v_rcp_f32_e32 v122, v122
	v_mov_b32_e32 v192, v239
	v_mul_f32_e32 v144, 0xbfb8aa3b, v147
	v_exp_f32_e32 v146, v144
	v_fmamk_f32 v116, v116, 0xbfb8aa3b, v28
	v_exp_f32_e32 v116, v116
	s_nop 0
	v_add_f32_e32 v116, 1.0, v116
	v_ashrrev_i32_e32 v169, 31, v168
	v_fmamk_f32 v123, v123, 0xbfb8aa3b, v47
	v_rcp_f32_e32 v116, v116
	v_exp_f32_e32 v123, v123
	v_cmp_lt_f32_e64 vcc, |v146|, s96
	v_mul_f32_e32 v116, v116, v188
	v_add_f32_e32 v123, 1.0, v123
	v_mov_b32_e32 v151, v243
	v_lshlrev_b64 v[144:145], 10, v[168:169]
	v_lshl_add_u64 v[144:145], v[144:145], 0, v[166:167]
	v_lshlrev_b64 v[148:149], 1, v[144:145]
	v_lshl_add_u64 v[144:145], s[30:31], 0, v[148:149]
	global_load_dwordx4 v[144:147], v[144:145], off
	v_rcp_f32_e32 v123, v123
	v_exp_f32_e32 v116, v116
	v_fmamk_f32 v112, v112, 0xbfb8aa3b, v32
	v_exp_f32_e32 v112, v112
	v_fmamk_f32 v113, v113, 0xbfb8aa3b, v33
	v_exp_f32_e32 v113, v113
	v_add_f32_e32 v112, 1.0, v112
	v_rcp_f32_e32 v112, v112
	v_add_f32_e32 v113, 1.0, v113
	v_rcp_f32_e32 v113, v113
	v_fmamk_f32 v108, v108, 0xbfb8aa3b, v40
	v_exp_f32_e32 v108, v108
	v_fmamk_f32 v104, v104, 0xbfb8aa3b, v44
	v_exp_f32_e32 v104, v104
	v_add_f32_e32 v108, 1.0, v108
	v_rcp_f32_e32 v108, v108
	v_add_f32_e32 v104, 1.0, v104
	v_rcp_f32_e32 v104, v104
	v_mul_f32_e32 v108, v108, v187
	v_exp_f32_e32 v108, v108
	v_fmamk_f32 v105, v105, 0xbfb8aa3b, v45
	v_exp_f32_e32 v105, v105
	v_fmamk_f32 v106, v106, 0xbfb8aa3b, v46
	v_exp_f32_e32 v106, v106
	v_add_f32_e32 v105, 1.0, v105
	v_rcp_f32_e32 v105, v105
	v_add_f32_e32 v106, 1.0, v106
	v_rcp_f32_e32 v106, v106
	v_fmamk_f32 v100, v100, 0xbfb8aa3b, v28
	v_exp_f32_e32 v100, v100
	v_fmamk_f32 v107, v107, 0xbfb8aa3b, v47
	v_exp_f32_e32 v107, v107
	v_add_f32_e32 v100, 1.0, v100
	v_rcp_f32_e32 v100, v100
	v_add_f32_e32 v107, 1.0, v107
	v_rcp_f32_e32 v107, v107
	v_mul_f32_e32 v100, v100, v188
	v_exp_f32_e32 v100, v100
	v_fmamk_f32 v96, v96, 0xbfb8aa3b, v32
	v_exp_f32_e32 v96, v96
	v_fmamk_f32 v97, v97, 0xbfb8aa3b, v33
	v_exp_f32_e32 v97, v97
	v_add_f32_e32 v96, 1.0, v96
	v_rcp_f32_e32 v96, v96
	v_add_f32_e32 v97, 1.0, v97
	v_rcp_f32_e32 v97, v97
	v_fmamk_f32 v92, v92, 0xbfb8aa3b, v40
	v_exp_f32_e32 v92, v92
	v_fmamk_f32 v88, v88, 0xbfb8aa3b, v44
	v_exp_f32_e32 v88, v88
	v_add_f32_e32 v92, 1.0, v92
	v_rcp_f32_e32 v92, v92
	v_add_f32_e32 v88, 1.0, v88
	v_rcp_f32_e32 v88, v88
	v_mul_f32_e32 v92, v92, v187
	v_exp_f32_e32 v92, v92
	v_fmamk_f32 v89, v89, 0xbfb8aa3b, v45
	v_exp_f32_e32 v89, v89
	v_fmamk_f32 v90, v90, 0xbfb8aa3b, v46
	v_exp_f32_e32 v90, v90
	v_add_f32_e32 v89, 1.0, v89
	s_waitcnt vmcnt(0)
	v_or_b32_e32 v250, 16, v168
	v_ashrrev_i32_e32 v251, 31, v250
	v_lshlrev_b64 v[250:251], 10, v[250:251]
	v_lshl_add_u64 v[250:251], v[250:251], 0, v[166:167]
	v_lshlrev_b64 v[250:251], 1, v[250:251]
	v_lshl_add_u64 v[252:253], s[30:31], 0, v[250:251]
	global_load_dwordx4 v[246:249], v[252:253], off
	v_lshlrev_b32_e32 v169, 16, v144
	v_and_b32_e32 v193, 0xffff0000, v144
	v_lshlrev_b32_e32 v196, 16, v147
	v_and_b32_e32 v144, 0xffff0000, v147
	v_sub_f32_e32 v147, 1.0, v140
	v_fma_f32 v140, -v140, v140, 1.0
	v_max_f32_e32 v140, 0, v140
	v_sqrt_f32_e32 v140, v140
	v_lshlrev_b32_e32 v194, 16, v145
	v_and_b32_e32 v145, 0xffff0000, v145
	v_lshlrev_b32_e32 v195, 16, v146
	v_mul_f32_e32 v136, v136, v140
	v_fmamk_f32 v140, v141, 0xbfb8aa3b, v41
	v_exp_f32_e32 v140, v140
	v_and_b32_e32 v146, 0xffff0000, v146
	v_mul_f32_e32 v136, v136, v169
	v_rcp_f32_e32 v89, v89
	v_add_f32_e32 v140, 1.0, v140
	v_rcp_f32_e32 v140, v140
	v_add_f32_e32 v90, 1.0, v90
	v_rcp_f32_e32 v90, v90
	v_mul_f32_e32 v140, v140, v190
	v_exp_f32_e32 v140, v140
	v_fmamk_f32 v84, v84, 0xbfb8aa3b, v28
	v_exp_f32_e32 v84, v84
	v_sub_f32_e32 v141, 1.0, v140
	v_fma_f32 v140, -v140, v140, 1.0
	v_max_f32_e32 v140, 0, v140
	v_sqrt_f32_e32 v140, v140
	v_add_f32_e32 v84, 1.0, v84
	v_fmamk_f32 v91, v91, 0xbfb8aa3b, v47
	v_rcp_f32_e32 v84, v84
	v_mul_f32_e32 v137, v137, v140
	v_fmamk_f32 v140, v142, 0xbfb8aa3b, v42
	v_exp_f32_e32 v140, v140
	v_mul_f32_e32 v137, v137, v193
	v_exp_f32_e32 v91, v91
	v_mul_f32_e32 v84, v84, v188
	v_add_f32_e32 v140, 1.0, v140
	v_rcp_f32_e32 v140, v140
	v_add_f32_e32 v91, 1.0, v91
	v_rcp_f32_e32 v91, v91
	v_mul_f32_e32 v140, v140, v191
	v_exp_f32_e32 v140, v140
	v_exp_f32_e32 v84, v84
	v_fmamk_f32 v80, v80, 0xbfb8aa3b, v32
	v_sub_f32_e32 v142, 1.0, v140
	v_fma_f32 v140, -v140, v140, 1.0
	v_max_f32_e32 v140, 0, v140
	v_sqrt_f32_e32 v140, v140
	v_exp_f32_e32 v80, v80
	v_fmamk_f32 v81, v81, 0xbfb8aa3b, v33
	v_mul_f32_e32 v138, v138, v140
	v_fmamk_f32 v140, v143, 0xbfb8aa3b, v43
	v_exp_f32_e32 v140, v140
	v_mul_f32_e32 v138, v138, v194
	v_add_f32_e32 v80, 1.0, v80
	v_rcp_f32_e32 v80, v80
	v_add_f32_e32 v140, 1.0, v140
	v_rcp_f32_e32 v140, v140
	v_exp_f32_e32 v81, v81
	v_fmamk_f32 v76, v76, 0xbfb8aa3b, v40
	v_mul_f32_e32 v140, v140, v192
	v_exp_f32_e32 v140, v140
	v_add_f32_e32 v81, 1.0, v81
	v_rcp_f32_e32 v81, v81
	v_exp_f32_e32 v76, v76
	v_sub_f32_e32 v143, 1.0, v140
	v_fma_f32 v140, -v140, v140, 1.0
	v_max_f32_e32 v140, 0, v140
	v_sqrt_f32_e32 v140, v140
	v_add_f32_e32 v76, 1.0, v76
	v_rcp_f32_e32 v76, v76
	v_mul_f32_e32 v139, v139, v140
	v_sub_f32_e32 v140, 1.0, v132
	v_fma_f32 v132, -v132, v132, 1.0
	v_max_f32_e32 v132, 0, v132
	v_sqrt_f32_e32 v132, v132
	v_mul_f32_e32 v139, v139, v145
	v_mul_f32_e32 v76, v76, v187
	v_mul_f32_e32 v128, v128, v132
	v_mul_f32_e32 v145, v128, v195
	v_fmamk_f32 v128, v133, 0xbfb8aa3b, v29
	v_exp_f32_e32 v128, v128
	v_exp_f32_e32 v76, v76
	v_fmamk_f32 v72, v72, 0xbfb8aa3b, v44
	v_exp_f32_e32 v72, v72
	v_add_f32_e32 v128, 1.0, v128
	v_rcp_f32_e32 v128, v128
	v_add_f32_e32 v72, 1.0, v72
	v_rcp_f32_e32 v72, v72
	v_mul_f32_e32 v128, v128, v189
	v_exp_f32_e32 v128, v128
	v_fmamk_f32 v73, v73, 0xbfb8aa3b, v45
	v_exp_f32_e32 v73, v73
	v_sub_f32_e32 v132, 1.0, v128
	v_fma_f32 v128, -v128, v128, 1.0
	v_max_f32_e32 v128, 0, v128
	v_sqrt_f32_e32 v128, v128
	v_add_f32_e32 v73, 1.0, v73
	v_rcp_f32_e32 v73, v73
	v_fmamk_f32 v74, v74, 0xbfb8aa3b, v46
	v_mul_f32_e32 v128, v129, v128
	v_mul_f32_e32 v146, v128, v146
	v_fmamk_f32 v128, v134, 0xbfb8aa3b, v30
	v_exp_f32_e32 v128, v128
	v_fmamk_f32 v129, v130, 0xbfb8aa3b, v34
	v_exp_f32_e32 v129, v129
	v_add_f32_e32 v128, 1.0, v128
	v_rcp_f32_e32 v128, v128
	v_exp_f32_e32 v74, v74
	v_add_f32_e32 v129, 1.0, v129
	v_rcp_f32_e32 v129, v129
	v_mul_f32_e32 v128, v128, v150
	v_exp_f32_e32 v128, v128
	v_add_f32_e32 v74, 1.0, v74
	v_rcp_f32_e32 v74, v74
	v_sub_f32_e32 v133, 1.0, v128
	v_fma_f32 v128, -v128, v128, 1.0
	v_max_f32_e32 v128, 0, v128
	v_sqrt_f32_e32 v128, v128
	v_fmamk_f32 v68, v68, 0xbfb8aa3b, v28
	v_exp_f32_e32 v68, v68
	v_mul_f32_e32 v128, v129, v128
	v_mul_f32_e32 v134, v128, v196
	v_fmamk_f32 v128, v135, 0xbfb8aa3b, v31
	v_exp_f32_e32 v128, v128
	v_fmamk_f32 v129, v131, 0xbfb8aa3b, v35
	v_exp_f32_e32 v129, v129
	v_add_f32_e32 v128, 1.0, v128
	v_rcp_f32_e32 v128, v128
	v_add_f32_e32 v68, 1.0, v68
	v_add_f32_e32 v129, 1.0, v129
	v_rcp_f32_e32 v129, v129
	v_mul_f32_e32 v128, v128, v151
	v_exp_f32_e32 v128, v128
	v_fmamk_f32 v75, v75, 0xbfb8aa3b, v47
	v_rcp_f32_e32 v68, v68
	v_exp_f32_e32 v75, v75
	v_sub_f32_e32 v131, 1.0, v128
	v_fma_f32 v128, -v128, v128, 1.0
	v_max_f32_e32 v128, 0, v128
	v_sqrt_f32_e32 v128, v128
	v_mul_f32_e32 v68, v68, v188
	v_add_f32_e32 v75, 1.0, v75
	v_mul_f32_e32 v128, v129, v128
	v_mul_f32_e32 v135, v128, v144
	v_cvt_pk_bf16_f32 v128, v147, v141
	v_cvt_pk_bf16_f32 v129, v142, v143
	v_cvt_pk_bf16_f32 v130, v140, v132
	v_cvt_pk_bf16_f32 v131, v133, v131
	v_lshl_add_u64 v[132:133], s[20:21], 0, v[148:149]
	global_store_dwordx4 v[132:133], v[128:131], off sc0 sc1
	s_nop 1
	v_cvt_pk_bf16_f32 v128, v136, v137
	v_cvt_pk_bf16_f32 v129, v138, v139
	v_cvt_pk_bf16_f32 v130, v145, v146
	v_cvt_pk_bf16_f32 v131, v134, v135
	v_lshl_add_u64 v[132:133], s[34:35], 0, v[148:149]
	global_store_dwordx4 v[132:133], v[128:131], off sc0 sc1
	s_nop 1
	v_or_b32_e32 v128, 16, v168
	v_ashrrev_i32_e32 v129, 31, v128
	v_lshlrev_b64 v[128:129], 10, v[128:129]
	v_lshl_add_u64 v[128:129], v[128:129], 0, v[166:167]
	v_lshlrev_b64 v[128:129], 1, v[128:129]
	v_lshl_add_u64 v[130:131], s[30:31], 0, v[128:129]
	v_rcp_f32_e32 v75, v75
	v_exp_f32_e32 v68, v68
	v_fmamk_f32 v64, v64, 0xbfb8aa3b, v32
	v_exp_f32_e32 v64, v64
	v_fmamk_f32 v65, v65, 0xbfb8aa3b, v33
	v_exp_f32_e32 v65, v65
	v_add_f32_e32 v64, 1.0, v64
	v_rcp_f32_e32 v64, v64
	v_add_f32_e32 v65, 1.0, v65
	v_rcp_f32_e32 v65, v65
	v_fmamk_f32 v60, v60, 0xbfb8aa3b, v40
	v_exp_f32_e32 v60, v60
	v_fmamk_f32 v56, v56, 0xbfb8aa3b, v44
	v_exp_f32_e32 v56, v56
	v_add_f32_e32 v60, 1.0, v60
	v_rcp_f32_e32 v60, v60
	v_add_f32_e32 v56, 1.0, v56
	v_rcp_f32_e32 v56, v56
	v_mul_f32_e32 v60, v60, v187
	v_exp_f32_e32 v60, v60
	v_fmamk_f32 v57, v57, 0xbfb8aa3b, v45
	v_exp_f32_e32 v57, v57
	v_fmamk_f32 v58, v58, 0xbfb8aa3b, v46
	v_exp_f32_e32 v58, v58
	v_add_f32_e32 v57, 1.0, v57
	v_rcp_f32_e32 v57, v57
	v_add_f32_e32 v58, 1.0, v58
	v_rcp_f32_e32 v58, v58
	v_fmamk_f32 v52, v52, 0xbfb8aa3b, v28
	v_exp_f32_e32 v52, v52
	v_fmamk_f32 v59, v59, 0xbfb8aa3b, v47
	v_exp_f32_e32 v59, v59
	v_add_f32_e32 v52, 1.0, v52
	v_rcp_f32_e32 v52, v52
	v_add_f32_e32 v59, 1.0, v59
	v_rcp_f32_e32 v59, v59
	v_mul_f32_e32 v52, v52, v188
	v_exp_f32_e32 v52, v52
	v_fmamk_f32 v48, v48, 0xbfb8aa3b, v32
	v_exp_f32_e32 v48, v48
	v_fmamk_f32 v49, v49, 0xbfb8aa3b, v33
	v_exp_f32_e32 v49, v49
	v_add_f32_e32 v48, 1.0, v48
	v_rcp_f32_e32 v48, v48
	v_add_f32_e32 v49, 1.0, v49
	v_rcp_f32_e32 v49, v49
	v_fmamk_f32 v36, v36, 0xbfb8aa3b, v40
	v_exp_f32_e32 v36, v36
	v_fmamk_f32 v24, v24, 0xbfb8aa3b, v44
	v_exp_f32_e32 v24, v24
	v_add_f32_e32 v36, 1.0, v36
	v_rcp_f32_e32 v36, v36
	v_add_f32_e32 v24, 1.0, v24
	v_rcp_f32_e32 v24, v24
	v_mul_f32_e32 v36, v36, v187
	v_exp_f32_e32 v36, v36
	v_fmamk_f32 v25, v25, 0xbfb8aa3b, v45
	v_exp_f32_e32 v25, v25
	v_fmamk_f32 v26, v26, 0xbfb8aa3b, v46
	v_exp_f32_e32 v26, v26
	v_add_f32_e32 v25, 1.0, v25
	v_rcp_f32_e32 v25, v25
	s_waitcnt vmcnt(2)
	v_mov_b32_e32 v130, v246
	v_mov_b32_e32 v131, v247
	v_mov_b32_e32 v132, v248
	v_mov_b32_e32 v133, v249
	v_or_b32_e32 v250, 32, v168
	v_ashrrev_i32_e32 v251, 31, v250
	v_lshlrev_b64 v[250:251], 10, v[250:251]
	v_lshl_add_u64 v[250:251], v[250:251], 0, v[166:167]
	v_lshlrev_b64 v[250:251], 1, v[250:251]
	v_lshl_add_u64 v[252:253], s[30:31], 0, v[250:251]
	global_load_dwordx4 v[246:249], v[252:253], off
	v_lshlrev_b32_e32 v134, 16, v130
	v_and_b32_e32 v135, 0xffff0000, v130
	v_lshlrev_b32_e32 v138, 16, v133
	v_and_b32_e32 v130, 0xffff0000, v133
	v_sub_f32_e32 v133, 1.0, v124
	v_fma_f32 v124, -v124, v124, 1.0
	v_max_f32_e32 v124, 0, v124
	v_sqrt_f32_e32 v124, v124
	v_lshlrev_b32_e32 v136, 16, v131
	v_and_b32_e32 v131, 0xffff0000, v131
	v_lshlrev_b32_e32 v137, 16, v132
	v_mul_f32_e32 v120, v120, v124
	v_fmamk_f32 v124, v125, 0xbfb8aa3b, v41
	v_exp_f32_e32 v124, v124
	v_and_b32_e32 v132, 0xffff0000, v132
	v_mul_f32_e32 v120, v120, v134
	v_add_f32_e32 v26, 1.0, v26
	v_add_f32_e32 v124, 1.0, v124
	v_rcp_f32_e32 v124, v124
	v_rcp_f32_e32 v26, v26
	v_fmamk_f32 v20, v20, 0xbfb8aa3b, v28
	v_mul_f32_e32 v124, v124, v190
	v_exp_f32_e32 v124, v124
	v_exp_f32_e32 v20, v20
	v_fmamk_f32 v27, v27, 0xbfb8aa3b, v47
	v_sub_f32_e32 v125, 1.0, v124
	v_fma_f32 v124, -v124, v124, 1.0
	v_max_f32_e32 v124, 0, v124
	v_sqrt_f32_e32 v124, v124
	v_add_f32_e32 v20, 1.0, v20
	v_rcp_f32_e32 v20, v20
	v_exp_f32_e32 v27, v27
	v_mul_f32_e32 v121, v121, v124
	v_fmamk_f32 v124, v126, 0xbfb8aa3b, v42
	v_exp_f32_e32 v124, v124
	v_mul_f32_e32 v121, v121, v135
	v_mul_f32_e32 v20, v20, v188
	v_add_f32_e32 v27, 1.0, v27
	v_add_f32_e32 v124, 1.0, v124
	v_rcp_f32_e32 v124, v124
	v_rcp_f32_e32 v27, v27
	v_mul_f32_e32 v124, v124, v191
	v_exp_f32_e32 v124, v124
	v_exp_f32_e32 v20, v20
	v_fmamk_f32 v16, v16, 0xbfb8aa3b, v32
	v_exp_f32_e32 v16, v16
	v_sub_f32_e32 v126, 1.0, v124
	v_fma_f32 v124, -v124, v124, 1.0
	v_max_f32_e32 v124, 0, v124
	v_sqrt_f32_e32 v124, v124
	v_add_f32_e32 v16, 1.0, v16
	v_rcp_f32_e32 v16, v16
	v_mul_f32_e32 v122, v122, v124
	v_fmamk_f32 v124, v127, 0xbfb8aa3b, v43
	v_exp_f32_e32 v124, v124
	v_mul_f32_e32 v122, v122, v136
	v_fmamk_f32 v17, v17, 0xbfb8aa3b, v33
	v_exp_f32_e32 v17, v17
	v_add_f32_e32 v124, 1.0, v124
	v_rcp_f32_e32 v124, v124
	v_add_f32_e32 v17, 1.0, v17
	v_rcp_f32_e32 v17, v17
	v_mul_f32_e32 v124, v124, v192
	v_exp_f32_e32 v124, v124
	v_fmamk_f32 v12, v12, 0xbfb8aa3b, v40
	v_exp_f32_e32 v12, v12
	v_sub_f32_e32 v127, 1.0, v124
	v_fma_f32 v124, -v124, v124, 1.0
	v_max_f32_e32 v124, 0, v124
	v_sqrt_f32_e32 v124, v124
	v_add_f32_e32 v12, 1.0, v12
	v_rcp_f32_e32 v12, v12
	v_fmamk_f32 v8, v8, 0xbfb8aa3b, v44
	v_mul_f32_e32 v123, v123, v124
	v_sub_f32_e32 v124, 1.0, v116
	v_fma_f32 v116, -v116, v116, 1.0
	v_max_f32_e32 v116, 0, v116
	v_sqrt_f32_e32 v116, v116
	v_mul_f32_e32 v123, v123, v131
	v_mul_f32_e32 v12, v12, v187
	v_mul_f32_e32 v112, v112, v116
	v_mul_f32_e32 v131, v112, v137
	v_fmamk_f32 v112, v117, 0xbfb8aa3b, v29
	v_exp_f32_e32 v112, v112
	v_exp_f32_e32 v12, v12
	v_exp_f32_e32 v8, v8
	v_add_f32_e32 v112, 1.0, v112
	v_rcp_f32_e32 v112, v112
	v_add_f32_e32 v8, 1.0, v8
	v_rcp_f32_e32 v8, v8
	v_fmamk_f32 v9, v9, 0xbfb8aa3b, v45
	v_mul_f32_e32 v112, v112, v189
	v_exp_f32_e32 v112, v112
	v_exp_f32_e32 v9, v9
	v_fmamk_f32 v10, v10, 0xbfb8aa3b, v46
	v_sub_f32_e32 v116, 1.0, v112
	v_fma_f32 v112, -v112, v112, 1.0
	v_max_f32_e32 v112, 0, v112
	v_sqrt_f32_e32 v112, v112
	v_add_f32_e32 v9, 1.0, v9
	v_rcp_f32_e32 v9, v9
	v_exp_f32_e32 v10, v10
	v_mul_f32_e32 v112, v113, v112
	v_mul_f32_e32 v132, v112, v132
	v_fmamk_f32 v112, v118, 0xbfb8aa3b, v30
	v_exp_f32_e32 v112, v112
	v_fmamk_f32 v113, v114, 0xbfb8aa3b, v34
	v_exp_f32_e32 v113, v113
	v_add_f32_e32 v112, 1.0, v112
	v_rcp_f32_e32 v112, v112
	v_add_f32_e32 v10, 1.0, v10
	v_add_f32_e32 v113, 1.0, v113
	v_rcp_f32_e32 v113, v113
	v_mul_f32_e32 v112, v112, v150
	v_exp_f32_e32 v112, v112
	v_rcp_f32_e32 v10, v10
	v_fmamk_f32 v4, v4, 0xbfb8aa3b, v28
	v_sub_f32_e32 v117, 1.0, v112
	v_fma_f32 v112, -v112, v112, 1.0
	v_max_f32_e32 v112, 0, v112
	v_sqrt_f32_e32 v112, v112
	v_exp_f32_e32 v4, v4
	v_fmamk_f32 v11, v11, 0xbfb8aa3b, v47
	v_mul_f32_e32 v112, v113, v112
	v_mul_f32_e32 v118, v112, v138
	v_fmamk_f32 v112, v119, 0xbfb8aa3b, v31
	v_exp_f32_e32 v112, v112
	v_fmamk_f32 v113, v115, 0xbfb8aa3b, v35
	v_exp_f32_e32 v113, v113
	v_add_f32_e32 v112, 1.0, v112
	v_rcp_f32_e32 v112, v112
	v_add_f32_e32 v4, 1.0, v4
	v_add_f32_e32 v113, 1.0, v113
	v_rcp_f32_e32 v113, v113
	v_mul_f32_e32 v112, v112, v151
	v_exp_f32_e32 v112, v112
	v_rcp_f32_e32 v4, v4
	v_exp_f32_e32 v11, v11
	v_sub_f32_e32 v115, 1.0, v112
	v_fma_f32 v112, -v112, v112, 1.0
	v_max_f32_e32 v112, 0, v112
	v_sqrt_f32_e32 v112, v112
	v_mul_f32_e32 v4, v4, v188
	v_add_f32_e32 v11, 1.0, v11
	v_mul_f32_e32 v112, v113, v112
	v_mul_f32_e32 v119, v112, v130
	v_cvt_pk_bf16_f32 v112, v133, v125
	v_cvt_pk_bf16_f32 v113, v126, v127
	v_cvt_pk_bf16_f32 v114, v124, v116
	v_cvt_pk_bf16_f32 v115, v117, v115
	v_lshl_add_u64 v[116:117], s[20:21], 0, v[128:129]
	global_store_dwordx4 v[116:117], v[112:115], off sc0 sc1
	s_nop 1
	v_cvt_pk_bf16_f32 v112, v120, v121
	v_cvt_pk_bf16_f32 v113, v122, v123
	v_cvt_pk_bf16_f32 v114, v131, v132
	v_cvt_pk_bf16_f32 v115, v118, v119
	v_lshl_add_u64 v[116:117], s[34:35], 0, v[128:129]
	global_store_dwordx4 v[116:117], v[112:115], off sc0 sc1
	s_nop 1
	v_or_b32_e32 v112, 32, v168
	v_ashrrev_i32_e32 v113, 31, v112
	v_lshlrev_b64 v[112:113], 10, v[112:113]
	v_lshl_add_u64 v[112:113], v[112:113], 0, v[166:167]
	v_lshlrev_b64 v[112:113], 1, v[112:113]
	v_lshl_add_u64 v[114:115], s[30:31], 0, v[112:113]
	v_rcp_f32_e32 v11, v11
	v_exp_f32_e32 v4, v4
	v_fmamk_f32 v0, v0, 0xbfb8aa3b, v32
	v_exp_f32_e32 v0, v0
	v_fmamk_f32 v1, v1, 0xbfb8aa3b, v33
	v_exp_f32_e32 v1, v1
	v_add_f32_e32 v0, 1.0, v0
	v_rcp_f32_e32 v0, v0
	v_add_f32_e32 v1, 1.0, v1
	v_rcp_f32_e32 v1, v1
	s_waitcnt vmcnt(2)
	v_mov_b32_e32 v114, v246
	v_mov_b32_e32 v115, v247
	v_mov_b32_e32 v116, v248
	v_mov_b32_e32 v117, v249
	v_or_b32_e32 v250, 48, v168
	v_ashrrev_i32_e32 v251, 31, v250
	v_lshlrev_b64 v[250:251], 10, v[250:251]
	v_lshl_add_u64 v[250:251], v[250:251], 0, v[166:167]
	v_lshlrev_b64 v[250:251], 1, v[250:251]
	v_lshl_add_u64 v[252:253], s[30:31], 0, v[250:251]
	global_load_dwordx4 v[246:249], v[252:253], off
	v_lshlrev_b32_e32 v118, 16, v114
	v_and_b32_e32 v119, 0xffff0000, v114
	v_lshlrev_b32_e32 v122, 16, v117
	v_and_b32_e32 v114, 0xffff0000, v117
	v_sub_f32_e32 v117, 1.0, v108
	v_fma_f32 v108, -v108, v108, 1.0
	v_max_f32_e32 v108, 0, v108
	v_sqrt_f32_e32 v108, v108
	v_lshlrev_b32_e32 v120, 16, v115
	v_and_b32_e32 v115, 0xffff0000, v115
	v_lshlrev_b32_e32 v121, 16, v116
	v_mul_f32_e32 v104, v104, v108
	v_fmamk_f32 v108, v109, 0xbfb8aa3b, v41
	v_exp_f32_e32 v108, v108
	v_and_b32_e32 v116, 0xffff0000, v116
	v_mul_f32_e32 v104, v104, v118
	v_add_f32_e32 v108, 1.0, v108
	v_rcp_f32_e32 v108, v108
	s_nop 0
	v_mul_f32_e32 v108, v108, v190
	v_exp_f32_e32 v108, v108
	s_nop 0
	v_sub_f32_e32 v109, 1.0, v108
	v_fma_f32 v108, -v108, v108, 1.0
	v_max_f32_e32 v108, 0, v108
	v_sqrt_f32_e32 v108, v108
	s_nop 0
	v_mul_f32_e32 v105, v105, v108
	v_fmamk_f32 v108, v110, 0xbfb8aa3b, v42
	v_exp_f32_e32 v108, v108
	v_mul_f32_e32 v105, v105, v119
	v_add_f32_e32 v108, 1.0, v108
	v_rcp_f32_e32 v108, v108
	s_nop 0
	v_mul_f32_e32 v108, v108, v191
	v_exp_f32_e32 v108, v108
	s_nop 0
	v_sub_f32_e32 v110, 1.0, v108
	v_fma_f32 v108, -v108, v108, 1.0
	v_max_f32_e32 v108, 0, v108
	v_sqrt_f32_e32 v108, v108
	s_nop 0
	v_mul_f32_e32 v106, v106, v108
	v_fmamk_f32 v108, v111, 0xbfb8aa3b, v43
	v_exp_f32_e32 v108, v108
	v_mul_f32_e32 v106, v106, v120
	v_add_f32_e32 v108, 1.0, v108
	v_rcp_f32_e32 v108, v108
	s_nop 0
	v_mul_f32_e32 v108, v108, v192
	v_exp_f32_e32 v108, v108
	s_nop 0
	v_sub_f32_e32 v111, 1.0, v108
	v_fma_f32 v108, -v108, v108, 1.0
	v_max_f32_e32 v108, 0, v108
	v_sqrt_f32_e32 v108, v108
	s_nop 0
	v_mul_f32_e32 v107, v107, v108
	v_sub_f32_e32 v108, 1.0, v100
	v_fma_f32 v100, -v100, v100, 1.0
	v_max_f32_e32 v100, 0, v100
	v_sqrt_f32_e32 v100, v100
	v_mul_f32_e32 v107, v107, v115
	v_mul_f32_e32 v96, v96, v100
	v_mul_f32_e32 v115, v96, v121
	v_fmamk_f32 v96, v101, 0xbfb8aa3b, v29
	v_exp_f32_e32 v96, v96
	s_nop 0
	v_add_f32_e32 v96, 1.0, v96
	v_rcp_f32_e32 v96, v96
	s_nop 0
	v_mul_f32_e32 v96, v96, v189
	v_exp_f32_e32 v96, v96
	s_nop 0
	v_sub_f32_e32 v100, 1.0, v96
	v_fma_f32 v96, -v96, v96, 1.0
	v_max_f32_e32 v96, 0, v96
	v_sqrt_f32_e32 v96, v96
	s_nop 0
	v_mul_f32_e32 v96, v97, v96
	v_mul_f32_e32 v116, v96, v116
	v_fmamk_f32 v96, v102, 0xbfb8aa3b, v30
	v_exp_f32_e32 v96, v96
	v_fmamk_f32 v97, v98, 0xbfb8aa3b, v34
	v_exp_f32_e32 v97, v97
	v_add_f32_e32 v96, 1.0, v96
	v_rcp_f32_e32 v96, v96
	v_add_f32_e32 v97, 1.0, v97
	v_rcp_f32_e32 v97, v97
	v_mul_f32_e32 v96, v96, v150
	v_exp_f32_e32 v96, v96
	s_nop 0
	v_sub_f32_e32 v101, 1.0, v96
	v_fma_f32 v96, -v96, v96, 1.0
	v_max_f32_e32 v96, 0, v96
	v_sqrt_f32_e32 v96, v96
	s_nop 0
	v_mul_f32_e32 v96, v97, v96
	v_mul_f32_e32 v102, v96, v122
	v_fmamk_f32 v96, v103, 0xbfb8aa3b, v31
	v_exp_f32_e32 v96, v96
	v_fmamk_f32 v97, v99, 0xbfb8aa3b, v35
	v_exp_f32_e32 v97, v97
	v_add_f32_e32 v96, 1.0, v96
	v_rcp_f32_e32 v96, v96
	v_add_f32_e32 v97, 1.0, v97
	v_rcp_f32_e32 v97, v97
	v_mul_f32_e32 v96, v96, v151
	v_exp_f32_e32 v96, v96
	s_nop 0
	v_sub_f32_e32 v99, 1.0, v96
	v_fma_f32 v96, -v96, v96, 1.0
	v_max_f32_e32 v96, 0, v96
	v_sqrt_f32_e32 v96, v96
	s_nop 0
	v_mul_f32_e32 v96, v97, v96
	v_mul_f32_e32 v103, v96, v114
	v_cvt_pk_bf16_f32 v96, v117, v109
	v_cvt_pk_bf16_f32 v97, v110, v111
	v_cvt_pk_bf16_f32 v98, v108, v100
	v_cvt_pk_bf16_f32 v99, v101, v99
	v_lshl_add_u64 v[100:101], s[20:21], 0, v[112:113]
	global_store_dwordx4 v[100:101], v[96:99], off sc0 sc1
	s_nop 1
	v_cvt_pk_bf16_f32 v96, v104, v105
	v_cvt_pk_bf16_f32 v97, v106, v107
	v_cvt_pk_bf16_f32 v98, v115, v116
	v_cvt_pk_bf16_f32 v99, v102, v103
	v_lshl_add_u64 v[100:101], s[34:35], 0, v[112:113]
	global_store_dwordx4 v[100:101], v[96:99], off sc0 sc1
	s_nop 1
	v_or_b32_e32 v96, 48, v168
	v_ashrrev_i32_e32 v97, 31, v96
	v_lshlrev_b64 v[96:97], 10, v[96:97]
	v_lshl_add_u64 v[96:97], v[96:97], 0, v[166:167]
	v_lshlrev_b64 v[96:97], 1, v[96:97]
	v_lshl_add_u64 v[98:99], s[30:31], 0, v[96:97]
	s_waitcnt vmcnt(2)
	v_mov_b32_e32 v98, v246
	v_mov_b32_e32 v99, v247
	v_mov_b32_e32 v100, v248
	v_mov_b32_e32 v101, v249
	v_lshl_add_u64 v[250:251], v[148:149], 0, s[8:9]
	v_lshl_add_u64 v[252:253], s[30:31], 0, v[250:251]
	global_load_dwordx4 v[246:249], v[252:253], off
	v_lshlrev_b32_e32 v102, 16, v98
	v_and_b32_e32 v103, 0xffff0000, v98
	v_lshlrev_b32_e32 v106, 16, v101
	v_and_b32_e32 v98, 0xffff0000, v101
	v_sub_f32_e32 v101, 1.0, v92
	v_fma_f32 v92, -v92, v92, 1.0
	v_max_f32_e32 v92, 0, v92
	v_sqrt_f32_e32 v92, v92
	v_lshlrev_b32_e32 v104, 16, v99
	v_and_b32_e32 v99, 0xffff0000, v99
	v_lshlrev_b32_e32 v105, 16, v100
	v_mul_f32_e32 v88, v88, v92
	v_fmamk_f32 v92, v93, 0xbfb8aa3b, v41
	v_exp_f32_e32 v92, v92
	v_and_b32_e32 v100, 0xffff0000, v100
	v_mul_f32_e32 v88, v88, v102
	v_add_f32_e32 v92, 1.0, v92
	v_rcp_f32_e32 v92, v92
	s_nop 0
	v_mul_f32_e32 v92, v92, v190
	v_exp_f32_e32 v92, v92
	s_nop 0
	v_sub_f32_e32 v93, 1.0, v92
	v_fma_f32 v92, -v92, v92, 1.0
	v_max_f32_e32 v92, 0, v92
	v_sqrt_f32_e32 v92, v92
	s_nop 0
	v_mul_f32_e32 v89, v89, v92
	v_fmamk_f32 v92, v94, 0xbfb8aa3b, v42
	v_exp_f32_e32 v92, v92
	v_mul_f32_e32 v89, v89, v103
	v_add_f32_e32 v92, 1.0, v92
	v_rcp_f32_e32 v92, v92
	s_nop 0
	v_mul_f32_e32 v92, v92, v191
	v_exp_f32_e32 v92, v92
	s_nop 0
	v_sub_f32_e32 v94, 1.0, v92
	v_fma_f32 v92, -v92, v92, 1.0
	v_max_f32_e32 v92, 0, v92
	v_sqrt_f32_e32 v92, v92
	s_nop 0
	v_mul_f32_e32 v90, v90, v92
	v_fmamk_f32 v92, v95, 0xbfb8aa3b, v43
	v_exp_f32_e32 v92, v92
	v_mul_f32_e32 v90, v90, v104
	v_add_f32_e32 v92, 1.0, v92
	v_rcp_f32_e32 v92, v92
	s_nop 0
	v_mul_f32_e32 v92, v92, v192
	v_exp_f32_e32 v92, v92
	s_nop 0
	v_sub_f32_e32 v95, 1.0, v92
	v_fma_f32 v92, -v92, v92, 1.0
	v_max_f32_e32 v92, 0, v92
	v_sqrt_f32_e32 v92, v92
	s_nop 0
	v_mul_f32_e32 v91, v91, v92
	v_sub_f32_e32 v92, 1.0, v84
	v_fma_f32 v84, -v84, v84, 1.0
	v_max_f32_e32 v84, 0, v84
	v_sqrt_f32_e32 v84, v84
	v_mul_f32_e32 v91, v91, v99
	v_mul_f32_e32 v80, v80, v84
	v_mul_f32_e32 v99, v80, v105
	v_fmamk_f32 v80, v85, 0xbfb8aa3b, v29
	v_exp_f32_e32 v80, v80
	s_nop 0
	v_add_f32_e32 v80, 1.0, v80
	v_rcp_f32_e32 v80, v80
	s_nop 0
	v_mul_f32_e32 v80, v80, v189
	v_exp_f32_e32 v80, v80
	s_nop 0
	v_sub_f32_e32 v84, 1.0, v80
	v_fma_f32 v80, -v80, v80, 1.0
	v_max_f32_e32 v80, 0, v80
	v_sqrt_f32_e32 v80, v80
	s_nop 0
	v_mul_f32_e32 v80, v81, v80
	v_mul_f32_e32 v100, v80, v100
	v_fmamk_f32 v80, v86, 0xbfb8aa3b, v30
	v_exp_f32_e32 v80, v80
	v_fmamk_f32 v81, v82, 0xbfb8aa3b, v34
	v_exp_f32_e32 v81, v81
	v_add_f32_e32 v80, 1.0, v80
	v_rcp_f32_e32 v80, v80
	v_add_f32_e32 v81, 1.0, v81
	v_rcp_f32_e32 v81, v81
	v_mul_f32_e32 v80, v80, v150
	v_exp_f32_e32 v80, v80
	s_nop 0
	v_sub_f32_e32 v85, 1.0, v80
	v_fma_f32 v80, -v80, v80, 1.0
	v_max_f32_e32 v80, 0, v80
	v_sqrt_f32_e32 v80, v80
	s_nop 0
	v_mul_f32_e32 v80, v81, v80
	v_mul_f32_e32 v86, v80, v106
	v_fmamk_f32 v80, v87, 0xbfb8aa3b, v31
	v_exp_f32_e32 v80, v80
	v_fmamk_f32 v81, v83, 0xbfb8aa3b, v35
	v_exp_f32_e32 v81, v81
	v_add_f32_e32 v80, 1.0, v80
	v_rcp_f32_e32 v80, v80
	v_add_f32_e32 v81, 1.0, v81
	v_rcp_f32_e32 v81, v81
	v_mul_f32_e32 v80, v80, v151
	v_exp_f32_e32 v80, v80
	s_nop 0
	v_sub_f32_e32 v83, 1.0, v80
	v_fma_f32 v80, -v80, v80, 1.0
	v_max_f32_e32 v80, 0, v80
	v_sqrt_f32_e32 v80, v80
	s_nop 0
	v_mul_f32_e32 v80, v81, v80
	v_mul_f32_e32 v87, v80, v98
	v_cvt_pk_bf16_f32 v80, v101, v93
	v_cvt_pk_bf16_f32 v81, v94, v95
	v_cvt_pk_bf16_f32 v82, v92, v84
	v_cvt_pk_bf16_f32 v83, v85, v83
	v_lshl_add_u64 v[84:85], s[20:21], 0, v[96:97]
	global_store_dwordx4 v[84:85], v[80:83], off sc0 sc1
	s_nop 1
	v_cvt_pk_bf16_f32 v80, v88, v89
	v_cvt_pk_bf16_f32 v81, v90, v91
	v_cvt_pk_bf16_f32 v82, v99, v100
	v_cvt_pk_bf16_f32 v83, v86, v87
	v_lshl_add_u64 v[84:85], s[34:35], 0, v[96:97]
	global_store_dwordx4 v[84:85], v[80:83], off sc0 sc1
	s_nop 1
	v_lshl_add_u64 v[80:81], v[148:149], 0, s[8:9]
	v_lshl_add_u64 v[82:83], s[30:31], 0, v[80:81]
	s_mov_b64 s[8:9], 0x48000
	s_waitcnt vmcnt(2)
	v_mov_b32_e32 v82, v246
	v_mov_b32_e32 v83, v247
	v_mov_b32_e32 v84, v248
	v_mov_b32_e32 v85, v249
	v_lshl_add_u64 v[250:251], v[148:149], 0, s[8:9]
	v_lshl_add_u64 v[252:253], s[30:31], 0, v[250:251]
	global_load_dwordx4 v[246:249], v[252:253], off
	v_lshlrev_b32_e32 v86, 16, v82
	v_and_b32_e32 v87, 0xffff0000, v82
	v_lshlrev_b32_e32 v90, 16, v85
	v_and_b32_e32 v82, 0xffff0000, v85
	v_sub_f32_e32 v85, 1.0, v76
	v_fma_f32 v76, -v76, v76, 1.0
	v_max_f32_e32 v76, 0, v76
	v_sqrt_f32_e32 v76, v76
	v_lshlrev_b32_e32 v88, 16, v83
	v_and_b32_e32 v83, 0xffff0000, v83
	v_lshlrev_b32_e32 v89, 16, v84
	v_mul_f32_e32 v72, v72, v76
	v_fmamk_f32 v76, v77, 0xbfb8aa3b, v41
	v_exp_f32_e32 v76, v76
	v_and_b32_e32 v84, 0xffff0000, v84
	v_mul_f32_e32 v72, v72, v86
	v_add_f32_e32 v76, 1.0, v76
	v_rcp_f32_e32 v76, v76
	s_nop 0
	v_mul_f32_e32 v76, v76, v190
	v_exp_f32_e32 v76, v76
	s_nop 0
	v_sub_f32_e32 v77, 1.0, v76
	v_fma_f32 v76, -v76, v76, 1.0
	v_max_f32_e32 v76, 0, v76
	v_sqrt_f32_e32 v76, v76
	s_nop 0
	v_mul_f32_e32 v73, v73, v76
	v_fmamk_f32 v76, v78, 0xbfb8aa3b, v42
	v_exp_f32_e32 v76, v76
	v_mul_f32_e32 v73, v73, v87
	v_add_f32_e32 v76, 1.0, v76
	v_rcp_f32_e32 v76, v76
	s_nop 0
	v_mul_f32_e32 v76, v76, v191
	v_exp_f32_e32 v76, v76
	s_nop 0
	v_sub_f32_e32 v78, 1.0, v76
	v_fma_f32 v76, -v76, v76, 1.0
	v_max_f32_e32 v76, 0, v76
	v_sqrt_f32_e32 v76, v76
	s_nop 0
	v_mul_f32_e32 v74, v74, v76
	v_fmamk_f32 v76, v79, 0xbfb8aa3b, v43
	v_exp_f32_e32 v76, v76
	v_mul_f32_e32 v74, v74, v88
	v_add_f32_e32 v76, 1.0, v76
	v_rcp_f32_e32 v76, v76
	s_nop 0
	v_mul_f32_e32 v76, v76, v192
	v_exp_f32_e32 v76, v76
	s_nop 0
	v_sub_f32_e32 v79, 1.0, v76
	v_fma_f32 v76, -v76, v76, 1.0
	v_max_f32_e32 v76, 0, v76
	v_sqrt_f32_e32 v76, v76
	s_nop 0
	v_mul_f32_e32 v75, v75, v76
	v_sub_f32_e32 v76, 1.0, v68
	v_fma_f32 v68, -v68, v68, 1.0
	v_max_f32_e32 v68, 0, v68
	v_sqrt_f32_e32 v68, v68
	v_mul_f32_e32 v75, v75, v83
	v_mul_f32_e32 v64, v64, v68
	v_mul_f32_e32 v83, v64, v89
	v_fmamk_f32 v64, v69, 0xbfb8aa3b, v29
	v_exp_f32_e32 v64, v64
	s_nop 0
	v_add_f32_e32 v64, 1.0, v64
	v_rcp_f32_e32 v64, v64
	s_nop 0
	v_mul_f32_e32 v64, v64, v189
	v_exp_f32_e32 v64, v64
	s_nop 0
	v_sub_f32_e32 v68, 1.0, v64
	v_fma_f32 v64, -v64, v64, 1.0
	v_max_f32_e32 v64, 0, v64
	v_sqrt_f32_e32 v64, v64
	s_nop 0
	v_mul_f32_e32 v64, v65, v64
	v_mul_f32_e32 v84, v64, v84
	v_fmamk_f32 v64, v70, 0xbfb8aa3b, v30
	v_exp_f32_e32 v64, v64
	v_fmamk_f32 v65, v66, 0xbfb8aa3b, v34
	v_exp_f32_e32 v65, v65
	v_add_f32_e32 v64, 1.0, v64
	v_rcp_f32_e32 v64, v64
	v_add_f32_e32 v65, 1.0, v65
	v_rcp_f32_e32 v65, v65
	v_mul_f32_e32 v64, v64, v150
	v_exp_f32_e32 v64, v64
	s_nop 0
	v_sub_f32_e32 v69, 1.0, v64
	v_fma_f32 v64, -v64, v64, 1.0
	v_max_f32_e32 v64, 0, v64
	v_sqrt_f32_e32 v64, v64
	s_nop 0
	v_mul_f32_e32 v64, v65, v64
	v_mul_f32_e32 v70, v64, v90
	v_fmamk_f32 v64, v71, 0xbfb8aa3b, v31
	v_exp_f32_e32 v64, v64
	v_fmamk_f32 v65, v67, 0xbfb8aa3b, v35
	v_exp_f32_e32 v65, v65
	v_add_f32_e32 v64, 1.0, v64
	v_rcp_f32_e32 v64, v64
	v_add_f32_e32 v65, 1.0, v65
	v_rcp_f32_e32 v65, v65
	v_mul_f32_e32 v64, v64, v151
	v_exp_f32_e32 v64, v64
	s_nop 0
	v_sub_f32_e32 v67, 1.0, v64
	v_fma_f32 v64, -v64, v64, 1.0
	v_max_f32_e32 v64, 0, v64
	v_sqrt_f32_e32 v64, v64
	s_nop 0
	v_mul_f32_e32 v64, v65, v64
	v_mul_f32_e32 v71, v64, v82
	v_cvt_pk_bf16_f32 v64, v85, v77
	v_cvt_pk_bf16_f32 v65, v78, v79
	v_cvt_pk_bf16_f32 v66, v76, v68
	v_cvt_pk_bf16_f32 v67, v69, v67
	v_lshl_add_u64 v[68:69], s[20:21], 0, v[80:81]
	global_store_dwordx4 v[68:69], v[64:67], off sc0 sc1
	s_nop 1
	v_cvt_pk_bf16_f32 v64, v72, v73
	v_cvt_pk_bf16_f32 v65, v74, v75
	v_cvt_pk_bf16_f32 v66, v83, v84
	v_cvt_pk_bf16_f32 v67, v70, v71
	v_lshl_add_u64 v[68:69], s[34:35], 0, v[80:81]
	global_store_dwordx4 v[68:69], v[64:67], off sc0 sc1
	s_nop 1
	v_lshl_add_u64 v[64:65], v[148:149], 0, s[8:9]
	v_lshl_add_u64 v[66:67], s[30:31], 0, v[64:65]
	s_mov_b64 s[8:9], 0x50000
	s_waitcnt vmcnt(2)
	v_mov_b32_e32 v66, v246
	v_mov_b32_e32 v67, v247
	v_mov_b32_e32 v68, v248
	v_mov_b32_e32 v69, v249
	v_lshl_add_u64 v[250:251], v[148:149], 0, s[8:9]
	v_lshl_add_u64 v[252:253], s[30:31], 0, v[250:251]
	global_load_dwordx4 v[246:249], v[252:253], off
	v_lshlrev_b32_e32 v70, 16, v66
	v_and_b32_e32 v71, 0xffff0000, v66
	v_lshlrev_b32_e32 v74, 16, v69
	v_and_b32_e32 v66, 0xffff0000, v69
	v_sub_f32_e32 v69, 1.0, v60
	v_fma_f32 v60, -v60, v60, 1.0
	v_max_f32_e32 v60, 0, v60
	v_sqrt_f32_e32 v60, v60
	v_lshlrev_b32_e32 v72, 16, v67
	v_and_b32_e32 v67, 0xffff0000, v67
	v_lshlrev_b32_e32 v73, 16, v68
	v_mul_f32_e32 v56, v56, v60
	v_fmamk_f32 v60, v61, 0xbfb8aa3b, v41
	v_exp_f32_e32 v60, v60
	v_and_b32_e32 v68, 0xffff0000, v68
	v_mul_f32_e32 v56, v56, v70
	v_add_f32_e32 v60, 1.0, v60
	v_rcp_f32_e32 v60, v60
	s_nop 0
	v_mul_f32_e32 v60, v60, v190
	v_exp_f32_e32 v60, v60
	s_nop 0
	v_sub_f32_e32 v61, 1.0, v60
	v_fma_f32 v60, -v60, v60, 1.0
	v_max_f32_e32 v60, 0, v60
	v_sqrt_f32_e32 v60, v60
	s_nop 0
	v_mul_f32_e32 v57, v57, v60
	v_fmamk_f32 v60, v62, 0xbfb8aa3b, v42
	v_exp_f32_e32 v60, v60
	v_mul_f32_e32 v57, v57, v71
	v_add_f32_e32 v60, 1.0, v60
	v_rcp_f32_e32 v60, v60
	s_nop 0
	v_mul_f32_e32 v60, v60, v191
	v_exp_f32_e32 v60, v60
	s_nop 0
	v_sub_f32_e32 v62, 1.0, v60
	v_fma_f32 v60, -v60, v60, 1.0
	v_max_f32_e32 v60, 0, v60
	v_sqrt_f32_e32 v60, v60
	s_nop 0
	v_mul_f32_e32 v58, v58, v60
	v_fmamk_f32 v60, v63, 0xbfb8aa3b, v43
	v_exp_f32_e32 v60, v60
	v_mul_f32_e32 v58, v58, v72
	v_add_f32_e32 v60, 1.0, v60
	v_rcp_f32_e32 v60, v60
	s_nop 0
	v_mul_f32_e32 v60, v60, v192
	v_exp_f32_e32 v60, v60
	s_nop 0
	v_sub_f32_e32 v63, 1.0, v60
	v_fma_f32 v60, -v60, v60, 1.0
	v_max_f32_e32 v60, 0, v60
	v_sqrt_f32_e32 v60, v60
	s_nop 0
	v_mul_f32_e32 v59, v59, v60
	v_sub_f32_e32 v60, 1.0, v52
	v_fma_f32 v52, -v52, v52, 1.0
	v_max_f32_e32 v52, 0, v52
	v_sqrt_f32_e32 v52, v52
	v_mul_f32_e32 v59, v59, v67
	v_mul_f32_e32 v48, v48, v52
	v_mul_f32_e32 v67, v48, v73
	v_fmamk_f32 v48, v53, 0xbfb8aa3b, v29
	v_exp_f32_e32 v48, v48
	s_nop 0
	v_add_f32_e32 v48, 1.0, v48
	v_rcp_f32_e32 v48, v48
	s_nop 0
	v_mul_f32_e32 v48, v48, v189
	v_exp_f32_e32 v48, v48
	s_nop 0
	v_sub_f32_e32 v52, 1.0, v48
	v_fma_f32 v48, -v48, v48, 1.0
	v_max_f32_e32 v48, 0, v48
	v_sqrt_f32_e32 v48, v48
	s_nop 0
	v_mul_f32_e32 v48, v49, v48
	v_mul_f32_e32 v68, v48, v68
	v_fmamk_f32 v48, v54, 0xbfb8aa3b, v30
	v_exp_f32_e32 v48, v48
	v_fmamk_f32 v49, v50, 0xbfb8aa3b, v34
	v_exp_f32_e32 v49, v49
	v_add_f32_e32 v48, 1.0, v48
	v_rcp_f32_e32 v48, v48
	v_add_f32_e32 v49, 1.0, v49
	v_rcp_f32_e32 v49, v49
	v_mul_f32_e32 v48, v48, v150
	v_exp_f32_e32 v48, v48
	s_nop 0
	v_sub_f32_e32 v53, 1.0, v48
	v_fma_f32 v48, -v48, v48, 1.0
	v_max_f32_e32 v48, 0, v48
	v_sqrt_f32_e32 v48, v48
	s_nop 0
	v_mul_f32_e32 v48, v49, v48
	v_mul_f32_e32 v54, v48, v74
	v_fmamk_f32 v48, v55, 0xbfb8aa3b, v31
	v_exp_f32_e32 v48, v48
	v_fmamk_f32 v49, v51, 0xbfb8aa3b, v35
	v_exp_f32_e32 v49, v49
	v_add_f32_e32 v48, 1.0, v48
	v_rcp_f32_e32 v48, v48
	v_add_f32_e32 v49, 1.0, v49
	v_rcp_f32_e32 v49, v49
	v_mul_f32_e32 v48, v48, v151
	v_exp_f32_e32 v48, v48
	s_nop 0
	v_sub_f32_e32 v51, 1.0, v48
	v_fma_f32 v48, -v48, v48, 1.0
	v_max_f32_e32 v48, 0, v48
	v_sqrt_f32_e32 v48, v48
	s_nop 0
	v_mul_f32_e32 v48, v49, v48
	v_mul_f32_e32 v55, v48, v66
	v_cvt_pk_bf16_f32 v48, v69, v61
	v_cvt_pk_bf16_f32 v49, v62, v63
	v_cvt_pk_bf16_f32 v50, v60, v52
	v_cvt_pk_bf16_f32 v51, v53, v51
	v_lshl_add_u64 v[52:53], s[20:21], 0, v[64:65]
	global_store_dwordx4 v[52:53], v[48:51], off sc0 sc1
	s_nop 1
	v_cvt_pk_bf16_f32 v48, v56, v57
	v_cvt_pk_bf16_f32 v49, v58, v59
	v_cvt_pk_bf16_f32 v50, v67, v68
	v_cvt_pk_bf16_f32 v51, v54, v55
	v_lshl_add_u64 v[52:53], s[34:35], 0, v[64:65]
	global_store_dwordx4 v[52:53], v[48:51], off sc0 sc1
	s_nop 1
	v_lshl_add_u64 v[48:49], v[148:149], 0, s[8:9]
	v_lshl_add_u64 v[50:51], s[30:31], 0, v[48:49]
	s_mov_b64 s[8:9], 0x58000
	s_waitcnt vmcnt(2)
	v_mov_b32_e32 v50, v246
	v_mov_b32_e32 v51, v247
	v_mov_b32_e32 v52, v248
	v_mov_b32_e32 v53, v249
	v_lshl_add_u64 v[250:251], v[148:149], 0, s[8:9]
	v_lshl_add_u64 v[252:253], s[30:31], 0, v[250:251]
	global_load_dwordx4 v[246:249], v[252:253], off
	v_lshlrev_b32_e32 v54, 16, v50
	v_and_b32_e32 v55, 0xffff0000, v50
	v_lshlrev_b32_e32 v58, 16, v53
	v_and_b32_e32 v50, 0xffff0000, v53
	v_sub_f32_e32 v53, 1.0, v36
	v_fma_f32 v36, -v36, v36, 1.0
	v_max_f32_e32 v36, 0, v36
	v_sqrt_f32_e32 v36, v36
	v_lshlrev_b32_e32 v56, 16, v51
	v_and_b32_e32 v51, 0xffff0000, v51
	v_lshlrev_b32_e32 v57, 16, v52
	v_mul_f32_e32 v24, v24, v36
	v_fmamk_f32 v36, v37, 0xbfb8aa3b, v41
	v_exp_f32_e32 v36, v36
	v_and_b32_e32 v52, 0xffff0000, v52
	v_mul_f32_e32 v24, v24, v54
	v_add_f32_e32 v36, 1.0, v36
	v_rcp_f32_e32 v36, v36
	s_nop 0
	v_mul_f32_e32 v36, v36, v190
	v_exp_f32_e32 v36, v36
	s_nop 0
	v_sub_f32_e32 v37, 1.0, v36
	v_fma_f32 v36, -v36, v36, 1.0
	v_max_f32_e32 v36, 0, v36
	v_sqrt_f32_e32 v36, v36
	s_nop 0
	v_mul_f32_e32 v25, v25, v36
	v_fmamk_f32 v36, v38, 0xbfb8aa3b, v42
	v_exp_f32_e32 v36, v36
	v_mul_f32_e32 v25, v25, v55
	v_add_f32_e32 v36, 1.0, v36
	v_rcp_f32_e32 v36, v36
	s_nop 0
	v_mul_f32_e32 v36, v36, v191
	v_exp_f32_e32 v36, v36
	s_nop 0
	v_sub_f32_e32 v38, 1.0, v36
	v_fma_f32 v36, -v36, v36, 1.0
	v_max_f32_e32 v36, 0, v36
	v_sqrt_f32_e32 v36, v36
	s_nop 0
	v_mul_f32_e32 v26, v26, v36
	v_fmamk_f32 v36, v39, 0xbfb8aa3b, v43
	v_exp_f32_e32 v36, v36
	v_mul_f32_e32 v26, v26, v56
	v_add_f32_e32 v36, 1.0, v36
	v_rcp_f32_e32 v36, v36
	s_nop 0
	v_mul_f32_e32 v36, v36, v192
	v_exp_f32_e32 v36, v36
	s_nop 0
	v_sub_f32_e32 v39, 1.0, v36
	v_fma_f32 v36, -v36, v36, 1.0
	v_max_f32_e32 v36, 0, v36
	v_sqrt_f32_e32 v36, v36
	s_nop 0
	v_mul_f32_e32 v27, v27, v36
	v_sub_f32_e32 v36, 1.0, v20
	v_fma_f32 v20, -v20, v20, 1.0
	v_max_f32_e32 v20, 0, v20
	v_sqrt_f32_e32 v20, v20
	v_mul_f32_e32 v27, v27, v51
	v_mul_f32_e32 v16, v16, v20
	v_mul_f32_e32 v51, v16, v57
	v_fmamk_f32 v16, v21, 0xbfb8aa3b, v29
	v_exp_f32_e32 v16, v16
	s_nop 0
	v_add_f32_e32 v16, 1.0, v16
	v_rcp_f32_e32 v16, v16
	s_nop 0
	v_mul_f32_e32 v16, v16, v189
	v_exp_f32_e32 v16, v16
	s_nop 0
	v_sub_f32_e32 v20, 1.0, v16
	v_fma_f32 v16, -v16, v16, 1.0
	v_max_f32_e32 v16, 0, v16
	v_sqrt_f32_e32 v16, v16
	s_nop 0
	v_mul_f32_e32 v16, v17, v16
	v_mul_f32_e32 v52, v16, v52
	v_fmamk_f32 v16, v22, 0xbfb8aa3b, v30
	v_exp_f32_e32 v16, v16
	v_fmamk_f32 v17, v18, 0xbfb8aa3b, v34
	v_exp_f32_e32 v17, v17
	v_add_f32_e32 v16, 1.0, v16
	v_rcp_f32_e32 v16, v16
	v_add_f32_e32 v17, 1.0, v17
	v_rcp_f32_e32 v17, v17
	v_mul_f32_e32 v16, v16, v150
	v_exp_f32_e32 v16, v16
	s_nop 0
	v_sub_f32_e32 v21, 1.0, v16
	v_fma_f32 v16, -v16, v16, 1.0
	v_max_f32_e32 v16, 0, v16
	v_sqrt_f32_e32 v16, v16
	s_nop 0
	v_mul_f32_e32 v16, v17, v16
	v_mul_f32_e32 v22, v16, v58
	v_fmamk_f32 v16, v23, 0xbfb8aa3b, v31
	v_exp_f32_e32 v16, v16
	v_fmamk_f32 v17, v19, 0xbfb8aa3b, v35
	v_exp_f32_e32 v17, v17
	v_add_f32_e32 v16, 1.0, v16
	v_rcp_f32_e32 v16, v16
	v_add_f32_e32 v17, 1.0, v17
	v_rcp_f32_e32 v17, v17
	v_mul_f32_e32 v16, v16, v151
	v_exp_f32_e32 v16, v16
	s_nop 0
	v_sub_f32_e32 v19, 1.0, v16
	v_fma_f32 v16, -v16, v16, 1.0
	v_max_f32_e32 v16, 0, v16
	v_sqrt_f32_e32 v16, v16
	s_nop 0
	v_mul_f32_e32 v16, v17, v16
	v_mul_f32_e32 v23, v16, v50
	v_cvt_pk_bf16_f32 v16, v53, v37
	v_cvt_pk_bf16_f32 v17, v38, v39
	v_cvt_pk_bf16_f32 v18, v36, v20
	v_cvt_pk_bf16_f32 v19, v21, v19
	v_lshl_add_u64 v[20:21], s[20:21], 0, v[48:49]
	global_store_dwordx4 v[20:21], v[16:19], off sc0 sc1
	s_nop 1
	v_cvt_pk_bf16_f32 v16, v24, v25
	v_cvt_pk_bf16_f32 v17, v26, v27
	v_cvt_pk_bf16_f32 v18, v51, v52
	v_cvt_pk_bf16_f32 v19, v22, v23
	v_lshl_add_u64 v[20:21], s[34:35], 0, v[48:49]
	global_store_dwordx4 v[20:21], v[16:19], off sc0 sc1
	s_nop 1
	v_lshl_add_u64 v[16:17], v[148:149], 0, s[8:9]
	v_lshl_add_u64 v[18:19], s[30:31], 0, v[16:17]
	s_waitcnt vmcnt(2)
	v_mov_b32_e32 v18, v246
	v_mov_b32_e32 v19, v247
	v_mov_b32_e32 v20, v248
	v_mov_b32_e32 v21, v249
	v_lshlrev_b32_e32 v22, 16, v18
	v_and_b32_e32 v23, 0xffff0000, v18
	v_lshlrev_b32_e32 v26, 16, v21
	v_and_b32_e32 v18, 0xffff0000, v21
	v_sub_f32_e32 v21, 1.0, v12
	v_fma_f32 v12, -v12, v12, 1.0
	v_max_f32_e32 v12, 0, v12
	v_sqrt_f32_e32 v12, v12
	v_lshlrev_b32_e32 v24, 16, v19
	v_and_b32_e32 v19, 0xffff0000, v19
	v_lshlrev_b32_e32 v25, 16, v20
	v_mul_f32_e32 v8, v8, v12
	v_fmamk_f32 v12, v13, 0xbfb8aa3b, v41
	v_exp_f32_e32 v12, v12
	v_and_b32_e32 v20, 0xffff0000, v20
	v_mul_f32_e32 v8, v8, v22
	v_add_f32_e32 v12, 1.0, v12
	v_rcp_f32_e32 v12, v12
	s_nop 0
	v_mul_f32_e32 v12, v12, v190
	v_exp_f32_e32 v12, v12
	s_nop 0
	v_sub_f32_e32 v13, 1.0, v12
	v_fma_f32 v12, -v12, v12, 1.0
	v_max_f32_e32 v12, 0, v12
	v_sqrt_f32_e32 v12, v12
	s_nop 0
	v_mul_f32_e32 v9, v9, v12
	v_fmamk_f32 v12, v14, 0xbfb8aa3b, v42
	v_exp_f32_e32 v12, v12
	v_mul_f32_e32 v9, v9, v23
	v_add_f32_e32 v12, 1.0, v12
	v_rcp_f32_e32 v12, v12
	s_nop 0
	v_mul_f32_e32 v12, v12, v191
	v_exp_f32_e32 v12, v12
	s_nop 0
	v_sub_f32_e32 v14, 1.0, v12
	v_fma_f32 v12, -v12, v12, 1.0
	v_max_f32_e32 v12, 0, v12
	v_sqrt_f32_e32 v12, v12
	s_nop 0
	v_mul_f32_e32 v10, v10, v12
	v_fmamk_f32 v12, v15, 0xbfb8aa3b, v43
	v_exp_f32_e32 v12, v12
	v_mul_f32_e32 v10, v10, v24
	v_add_f32_e32 v12, 1.0, v12
	v_rcp_f32_e32 v12, v12
	s_nop 0
	v_mul_f32_e32 v12, v12, v192
	v_exp_f32_e32 v12, v12
	s_nop 0
	v_sub_f32_e32 v15, 1.0, v12
	v_fma_f32 v12, -v12, v12, 1.0
	v_max_f32_e32 v12, 0, v12
	v_sqrt_f32_e32 v12, v12
	s_nop 0
	v_mul_f32_e32 v11, v11, v12
	v_sub_f32_e32 v12, 1.0, v4
	v_fma_f32 v4, -v4, v4, 1.0
	v_max_f32_e32 v4, 0, v4
	v_sqrt_f32_e32 v4, v4
	v_mul_f32_e32 v11, v11, v19
	v_mul_f32_e32 v0, v0, v4
	v_mul_f32_e32 v19, v0, v25
	v_fmamk_f32 v0, v5, 0xbfb8aa3b, v29
	v_exp_f32_e32 v0, v0
	s_nop 0
	v_add_f32_e32 v0, 1.0, v0
	v_rcp_f32_e32 v0, v0
	s_nop 0
	v_mul_f32_e32 v0, v0, v189
	v_exp_f32_e32 v0, v0
	s_nop 0
	v_sub_f32_e32 v4, 1.0, v0
	v_fma_f32 v0, -v0, v0, 1.0
	v_max_f32_e32 v0, 0, v0
	v_sqrt_f32_e32 v0, v0
	s_nop 0
	v_mul_f32_e32 v0, v1, v0
	v_mul_f32_e32 v20, v0, v20
	v_fmamk_f32 v0, v6, 0xbfb8aa3b, v30
	v_exp_f32_e32 v0, v0
	v_fmamk_f32 v1, v2, 0xbfb8aa3b, v34
	v_exp_f32_e32 v1, v1
	v_add_f32_e32 v0, 1.0, v0
	v_rcp_f32_e32 v0, v0
	v_add_f32_e32 v1, 1.0, v1
	v_rcp_f32_e32 v1, v1
	v_mul_f32_e32 v0, v0, v150
	v_exp_f32_e32 v0, v0
	s_nop 0
	v_sub_f32_e32 v5, 1.0, v0
	v_fma_f32 v0, -v0, v0, 1.0
	v_max_f32_e32 v0, 0, v0
	v_sqrt_f32_e32 v0, v0
	s_nop 0
	v_mul_f32_e32 v0, v1, v0
	v_mul_f32_e32 v6, v0, v26
	v_fmamk_f32 v0, v7, 0xbfb8aa3b, v31
	v_exp_f32_e32 v0, v0
	v_fmamk_f32 v1, v3, 0xbfb8aa3b, v35
	v_exp_f32_e32 v1, v1
	v_add_f32_e32 v0, 1.0, v0
	v_rcp_f32_e32 v0, v0
	v_add_f32_e32 v1, 1.0, v1
	v_rcp_f32_e32 v1, v1
	v_mul_f32_e32 v0, v0, v151
	v_exp_f32_e32 v0, v0
	s_nop 0
	v_sub_f32_e32 v3, 1.0, v0
	v_fma_f32 v0, -v0, v0, 1.0
	v_max_f32_e32 v0, 0, v0
	v_sqrt_f32_e32 v0, v0
	s_nop 0
	v_mul_f32_e32 v0, v1, v0
	v_mul_f32_e32 v7, v0, v18
	v_cvt_pk_bf16_f32 v0, v21, v13
	v_cvt_pk_bf16_f32 v1, v14, v15
	v_cvt_pk_bf16_f32 v2, v12, v4
	v_cvt_pk_bf16_f32 v3, v5, v3
	v_lshl_add_u64 v[4:5], s[20:21], 0, v[16:17]
	global_store_dwordx4 v[4:5], v[0:3], off sc0 sc1
	s_nop 1
	v_cvt_pk_bf16_f32 v0, v8, v9
	v_cvt_pk_bf16_f32 v1, v10, v11
	v_cvt_pk_bf16_f32 v2, v19, v20
	v_cvt_pk_bf16_f32 v3, v6, v7
	v_lshl_add_u64 v[4:5], s[34:35], 0, v[16:17]
	global_store_dwordx4 v[4:5], v[0:3], off sc0 sc1
	s_nop 1
	s_nop 0
	s_mov_b64 s[36:37], exec
	v_readlane_b32 s8, v254, 0
	v_readlane_b32 s9, v254, 1
	s_and_b64 s[8:9], s[36:37], s[8:9]
	s_mov_b64 exec, s[8:9]
	s_cbranch_execz .LBB0_464
	s_mov_b64 s[38:39], exec
	v_mbcnt_lo_u32_b32 v0, s38, 0
	v_mbcnt_hi_u32_b32 v0, s39, v0
	v_cmp_eq_u32_e32 vcc, 0, v0
	s_and_b64 s[8:9], exec, vcc
	s_mov_b64 exec, s[8:9]
	s_cbranch_execz .LBB0_464
	s_lshl_b32 s0, s0, 6
	s_ashr_i32 s1, s0, 31
	s_lshl_b64 s[0:1], s[0:1], 2
	v_readlane_b32 s4, v254, 51
	v_readlane_b32 s5, v254, 52
	s_add_u32 s0, s4, s0
	s_addc_u32 s1, s5, s1
	s_bcnt1_i32_b64 s8, s[38:39]
	v_mov_b32_e32 v0, s8
	s_sub_u32 s98, s0, 1
	s_subb_u32 s99, s1, 0
